# windowed-attention tile loops: K-row loads of pieces 1..3 use a running 64-bit pointer instead of compare+select+add+64-bit multiply
# baseline (speedup 1.0000x reference)
; DI int ltid() { int t = threadIdx.x & 255; asm volatile("" : "+v"(t)); return t; }
; template <int MODE>
; DI void attn64_wave(const Params& p, int layer, int b, int hq, int qrow0, int t0, const float* rpb_lds, unsigned char* wlds) {
;   constexpr bool isC = (MODE == 0 || MODE == 2);
;   const int lane = ltid() & 63, qi = lane & 31, hh = lane >> 5;
;   const int pr = (qi & 19) | ((qi & 4) << 1) | ((qi & 8) >> 1);
;   const float* gqp = (isC ? p.na_q_gain : p.sw_q_gain) + layer * 64;
;   const float* gkp = (isC ? p.na_k_gain : p.sw_k_gain) + layer * 64;
;   const float gq = wave_max(fabsf(gqp[lane])), gk = wave_max(fabsf(gkp[lane]));
;   const float negM2 = -(0.125f * LOG2E * 64.f * 1.02f) * gq * gk;
;   const int kvh = isC ? hq : (hq >> 1);
;   const int qcol = isC ? 2048 + 64 * hq : 2816 + 64 * hq;
;   const int kcol = isC ? 2304 + 64 * hq : 3072 + 64 * kvh;
;   const bf16_t* vt = isC ? p.VtC + (size_t)(b * 4 + hq) * 64 * UA : p.VtD + (size_t)(b * 2 + kvh) * 64 * UA;
;   const bf16_t* qp = p.P + (size_t)(qrow0 + qi) * NP + qcol + 8 * hh;
;   bf16x8 qf[4];
; #pragma unroll
;   for (int ks = 0; ks < 4; ++ks) qf[ks] = *(const bf16x8*)(qp + ks * 16);
;   f32x16 o[2];
; #pragma unroll
;   for (int dh = 0; dh < 2; ++dh)
; #pragma unroll
;     for (int i = 0; i < 16; ++i) o[dh][i] = 0.f;
;   float ls = 0.f;
;   constexpr int NT = MODE == 0 ? 24 : (MODE == 1 ? 18 : 8);
;   const int r = t0 >> 6, c = (t0 & 63) + qi;
;   const int rs = min(max(r - 4, 0), 248), ws = min(max(c - 8, 0), 48);
;   const float* rpb = rpb_lds + hq * 465;
;   const int qt = t0 + qi;
.LBB0_337:
	s_nop 3
	v_mov_b32_e32 v2, v212
	v_readlane_b32 s0, v255, 0
	v_and_b32_e32 v6, 63, v2
	v_lshlrev_b32_e32 v0, 2, v6
	v_readlane_b32 s1, v255, 1
	v_cmp_lt_i32_e32 vcc, v218, v217
	s_sub_i32 s2, s40, s48
	s_bfe_u32 s3, s2, 0x20007
	v_cndmask_b32_e32 v7, v216, v218, vcc
	v_cmp_lt_i32_e32 vcc, v219, v217
	global_load_dword v4, v0, s[0:1]
	v_readlane_b32 s0, v255, 2
	v_readlane_b32 s1, v255, 3
	v_cndmask_b32_e32 v8, v216, v219, vcc
	v_cmp_lt_i32_e32 vcc, v220, v217
	s_ashr_i32 s26, s2, 9
	s_lshl_b32 s2, s2, 7
	v_cndmask_b32_e32 v9, v216, v220, vcc
	global_load_dword v5, v0, s[0:1]
	v_cmp_lt_i32_e32 vcc, v221, v217
	s_and_b32 s2, s2, 0x3f80
	v_lshlrev_b32_e32 v13, 1, v2
	v_cndmask_b32_e32 v10, v216, v221, vcc
	v_cmp_lt_i32_e32 vcc, v222, v217
	v_lshrrev_b32_e32 v14, 1, v2
	s_lshl_b32 s27, s26, 14
	v_cndmask_b32_e32 v11, v216, v222, vcc
	v_cmp_lt_i32_e32 vcc, v223, v217
	v_and_b32_e32 v15, 19, v2
	v_lshlrev_b32_e32 v16, 4, v2
	v_cndmask_b32_e32 v12, v216, v223, vcc
	v_add_u32_e32 v18, s2, v152
	v_and_b32_e32 v13, 8, v13
	v_and_b32_e32 v14, 4, v14
	v_lshlrev_b32_e32 v133, 2, v7
	v_lshlrev_b32_e32 v7, 2, v8
	v_lshlrev_b32_e32 v8, 2, v9
	v_lshlrev_b32_e32 v9, 2, v10
	v_lshlrev_b32_e32 v10, 2, v11
	v_lshlrev_b32_e32 v11, 2, v12
	v_and_b32_e32 v12, 31, v2
	v_bfe_u32 v155, v2, 5, 1
	v_bfe_u32 v134, v2, 3, 3
	v_bfe_u32 v17, v2, 2, 4
	v_and_b32_e32 v2, 0x70, v16
	v_add_u32_e32 v16, s27, v18
	v_or3_b32 v13, v15, v13, v14
	v_ashrrev_i32_e32 v14, 6, v18
	v_or_b32_e32 v144, v12, v16
	v_max_i32_e32 v16, 4, v14
	v_add_u32_e32 v16, -4, v16
	v_min_u32_e32 v136, 0xf8, v16
	s_lshl_b32 s22, s3, 6
	v_mov_b64_e32 v[0:1], s[78:79]
	s_lshl_b32 s24, s26, 2
	v_writelane_b32 v255, s22, 10
	s_or_b32 s2, s24, s3
	v_mad_i64_i32 v[0:1], s[24:25], v144, s20, v[0:1]
	v_writelane_b32 v255, s23, 11
	s_lshl_b32 s22, s3, 7
	v_lshlrev_b32_e32 v192, 4, v155
	v_lshl_add_u64 v[0:1], v[0:1], 0, s[22:23]
	v_lshl_add_u64 v[0:1], v[0:1], 0, v[192:193]
	s_mul_i32 s28, s3, 0x744
	s_mul_hi_i32 s3, s2, 0x208000
	s_mul_i32 s2, s2, 0x208000
	s_add_u32 s2, s84, s2
	s_addc_u32 s3, s85, s3
	s_add_i32 s28, s90, s28
	s_add_u32 s24, s78, s22
	v_mov_b32_e32 v3, v193
	s_addc_u32 s25, s79, 0
	s_lshl_b32 s42, s26, 8
	v_lshl_add_u64 v[2:3], s[24:25], 0, v[2:3]
	s_mov_b64 s[0:1], 0x1200
	s_add_i32 s42, s42, 0x8000
	v_lshl_add_u64 v[128:129], v[2:3], 0, s[0:1]
	v_or_b32_e32 v19, v12, v154
	v_sub_u32_e64 v15, v19, 8 clamp
	v_lshlrev_b32_e32 v135, 3, v155
	v_min_u32_e32 v15, 48, v15
	v_cmp_ge_u32_e64 s[0:1], v135, v15
	v_add_u32_e32 v48, 16, v15
	s_add_i32 s22, s27, 0xffffff00
	v_writelane_b32 v255, s0, 12
	v_or_b32_e32 v49, 50, v135
	v_or_b32_e32 v50, 51, v135
	v_writelane_b32 v255, s1, 13
	v_or_b32_e32 v51, 52, v135
	s_waitcnt vmcnt(1)
	v_and_b32_e32 v18, 0x7fffffff, v4
	ds_bpermute_b32 v18, v133, v18
	v_max_f32_e64 v4, |v4|, |v4|
	v_or_b32_e32 v52, 53, v135
	v_or_b32_e32 v53, 54, v135
	v_or_b32_e32 v54, 55, v135
	s_waitcnt lgkmcnt(0)
	v_max_f32_e32 v18, v18, v18
	v_max_f32_e32 v4, v4, v18
	s_waitcnt vmcnt(0)
	v_and_b32_e32 v20, 0x7fffffff, v5
	ds_bpermute_b32 v20, v133, v20
	v_max_f32_e64 v5, |v5|, |v5|
	ds_bpermute_b32 v18, v7, v4
	v_mov_b32_e32 v138, 0
	s_mov_b32 s43, 0
	s_waitcnt lgkmcnt(1)
	v_max_f32_e32 v20, v20, v20
	v_max_f32_e32 v5, v5, v20
	ds_bpermute_b32 v7, v7, v5
	s_waitcnt lgkmcnt(1)
	v_max_f32_e32 v16, v18, v18
	v_max_f32_e32 v16, v4, v16
	ds_bpermute_b32 v18, v8, v16
	s_mov_b32 s41, 32
	s_waitcnt lgkmcnt(1)
	v_max_f32_e32 v7, v7, v7
	v_max_f32_e32 v7, v5, v7
	ds_bpermute_b32 v8, v8, v7
	s_waitcnt lgkmcnt(1)
	v_max_f32_e32 v18, v18, v18
	v_max_f32_e32 v16, v16, v18
	v_lshl_add_u64 v[4:5], v[0:1], 0, s[66:67]
	v_add_co_u32_e32 v0, vcc, s63, v0
	s_waitcnt lgkmcnt(0)
	v_max_f32_e32 v8, v8, v8
	v_max_f32_e32 v7, v7, v8
	ds_bpermute_b32 v8, v9, v16
	ds_bpermute_b32 v9, v9, v7
	v_addc_co_u32_e32 v1, vcc, 0, v1, vcc
	global_load_dwordx4 v[64:67], v[4:5], off offset:32
	global_load_dwordx4 v[68:71], v[4:5], off offset:64
	s_waitcnt lgkmcnt(1)
	v_max_f32_e32 v8, v8, v8
	s_waitcnt lgkmcnt(0)
	v_max_f32_e32 v9, v9, v9
	v_max_f32_e32 v8, v16, v8
	v_max_f32_e32 v7, v7, v9
	ds_bpermute_b32 v9, v10, v8
	ds_bpermute_b32 v10, v10, v7
	global_load_dwordx4 v[72:75], v[0:1], off
	global_load_dwordx4 v[76:79], v[4:5], off offset:96
	v_ashrrev_i32_e32 v145, 31, v144
	s_mov_b32 s89, 0x82000
	s_waitcnt lgkmcnt(1)
	v_max_f32_e32 v9, v9, v9
	s_waitcnt lgkmcnt(0)
	v_max_f32_e32 v10, v10, v10
	v_max_f32_e32 v8, v8, v9
	v_max_f32_e32 v7, v7, v10
	ds_bpermute_b32 v9, v11, v8
	ds_bpermute_b32 v10, v11, v7
	s_mov_b32 s48, 0x104000
	s_mov_b32 s49, 0x186000
	v_sub_u32_e32 v137, v136, v14
	s_waitcnt lgkmcnt(1)
	v_max_f32_e32 v0, v9, v9
	s_waitcnt lgkmcnt(0)
; template <int MODE>
; DI void attn64_wave(const Params& p, int layer, int b, int hq, int qrow0, int t0, const float* rpb_lds, unsigned char* wlds) {
;     ...
;   f32x16 o[2];
; #pragma unroll
;   for (int dh = 0; dh < 2; ++dh)
; #pragma unroll
;     for (int i = 0; i < 16; ++i) o[dh][i] = 0.f;
;   float ls = 0.f;
;   constexpr int NT = MODE == 0 ? 24 : (MODE == 1 ? 18 : 8);
;   const int r = t0 >> 6, c = (t0 & 63) + qi;
;   const int rs = min(max(r - 4, 0), 248), ws = min(max(c - 8, 0), 48);
;   const float* rpb = rpb_lds + hq * 465;
;   const int qt = t0 + qi;
;   auto tile_u = [&](int t) -> int {
;     if (t < 8) return 32 * t;
;     if (MODE == 0) return CTX + (rs + ((t - 8) >> 1)) * 64 + ((t - 8) & 1) * 32;
;     const int kt0 = t0 - 128 + 32 * (t - 8);
;     return CTX + min(max(kt0, 0), SEQ - 32);
;   };
;   auto load_tile = [&](Frag64& f, int t) { frag64_load(f, p.P, vt, b, tile_u(t), kcol, lane); };
;   unsigned char* Kw = wlds; unsigned char* Vw = wlds + W64_KB;
;   auto compute_tile = [&](const Frag64& f, int t) {
; #pragma unroll
;     for (int i = 0; i < 4; ++i) {
;       *(u32x4*)(Kw + ((lane >> 3) + 8 * i) * LDS_STRIDE + (lane & 7) * 16) = f.k[i];
;       *(u32x4*)(Vw + ((lane >> 2) + 16 * i) * W64_VSTR + (lane & 3) * 16) = f.v[i];
;     }
;     bf16x8 kf[4], vf[2][2];
; #pragma unroll
;     for (int ks = 0; ks < 4; ++ks) kf[ks] = __builtin_bit_cast(bf16x8, *(const u32x4*)(Kw + pr * LDS_STRIDE + (16 * ks + 8 * hh) * 2));
; #pragma unroll
;     for (int dh = 0; dh < 2; ++dh)
; #pragma unroll
;       for (int s2 = 0; s2 < 2; ++s2) vf[dh][s2] = __builtin_bit_cast(bf16x8, *(const u32x4*)(Vw + (32 * dh + qi) * W64_VSTR + (16 * s2 + 8 * hh) * 2));
;     f32x16 s;
; #pragma unroll
;     for (int i = 0; i < 16; ++i) s[i] = negM2;
; #pragma unroll
;     for (int ks = 0; ks < 4; ++ks) s = MFMA32(kf[ks], qf[ks], s);
;     float pe[16];
;     if (t < 8) {
; #pragma unroll
;       for (int i = 0; i < 16; ++i) pe[i] = fexp2(s[i]);
;     } else if (MODE == 0) {
;       const int kr = rs + ((t - 8) >> 1), hf = (t - 8) & 1;
;       const float* rrow = rpb + (kr - r + 7) * 31 + 15 - c;
; #pragma unroll
;       for (int i = 0; i < 16; ++i) {
;         const int kc = hf * 32 + 16 * (i >> 3) + 8 * hh + (i & 7);
;         const bool valid = (kc >= ws) && (kc < ws + 16);
;         const int kcc = min(max(kc, ws), ws + 15);
	v_max_f32_e32 v1, v10, v10
	v_max_f32_e32 v0, v8, v0
	v_max_f32_e32 v1, v7, v1
	v_mul_f32_e32 v0, 0xc13c5bb7, v0
	v_lshlrev_b32_e32 v8, 4, v6
	v_mul_f32_e32 v32, v0, v1
	v_and_b32_e32 v0, 48, v8
	v_mov_b32_e32 v1, v193
	v_lshl_add_u64 v[2:3], s[2:3], 0, v[0:1]
	v_or_b32_e32 v1, s42, v134
	v_mul_u32_u24_e32 v6, 0x8200, v17
	v_mov_b32_e32 v7, v193
	v_lshl_add_u64 v[130:131], v[2:3], 0, v[6:7]
	v_or_b32_e32 v2, 8, v1
	v_mad_u64_u32 v[4:5], s[2:3], v1, s20, v[128:129]
	v_mad_u64_u32 v[2:3], s[2:3], v2, s20, v[128:129]
	global_load_dwordx4 v[80:83], v[130:131], off
	global_load_dwordx4 v[84:87], v[4:5], off
	global_load_dwordx4 v[88:91], v[2:3], off
	v_add_co_u32_e32 v2, vcc, s61, v130
	v_or_b32_e32 v6, 1, v135
	s_nop 0
	v_addc_co_u32_e32 v3, vcc, 0, v131, vcc
	global_load_dwordx4 v[92:95], v[2:3], off
	v_or_b32_e32 v2, 16, v1
	v_mad_u64_u32 v[2:3], s[2:3], v2, s20, v[128:129]
	global_load_dwordx4 v[96:99], v[2:3], off
	v_add_co_u32_e32 v2, vcc, s62, v130
	v_or_b32_e32 v1, 24, v1
	s_nop 0
	v_addc_co_u32_e32 v3, vcc, 0, v131, vcc
	global_load_dwordx4 v[100:103], v[2:3], off
	v_mad_u64_u32 v[2:3], s[2:3], v1, s20, v[128:129]
	global_load_dwordx4 v[104:107], v[2:3], off
	v_add_co_u32_e32 v2, vcc, s64, v130
	v_cmp_ge_u32_e64 s[0:1], v6, v15
	s_nop 0
	v_addc_co_u32_e32 v3, vcc, 0, v131, vcc
	global_load_dwordx4 v[108:111], v[2:3], off
	v_writelane_b32 v255, s0, 14
	v_or_b32_e32 v6, 2, v135
	v_cmp_lt_u32_e32 vcc, v135, v15
	v_writelane_b32 v255, s1, 15
	v_cmp_ge_u32_e64 s[0:1], v6, v15
	v_or_b32_e32 v6, 3, v135
	v_mad_u32_u24 v1, v134, s59, v153
	v_writelane_b32 v255, s0, 16
	v_and_b32_e32 v2, 0x70, v8
	v_mad_u32_u24 v3, v17, s60, v153
	v_writelane_b32 v255, s1, 17
	v_cmp_ge_u32_e64 s[0:1], v6, v15
	v_or_b32_e32 v6, 4, v135
	v_mad_u32_u24 v4, v13, s59, v153
	v_writelane_b32 v255, s0, 18
	v_mad_u32_u24 v5, v12, s60, v153
	v_mov_b32_e32 v33, v32
	v_writelane_b32 v255, s1, 19
	v_cmp_ge_u32_e64 s[0:1], v6, v15
	v_or_b32_e32 v6, 5, v135
	v_mov_b32_e32 v34, v32
	v_writelane_b32 v255, s0, 20
	v_mov_b32_e32 v35, v32
	v_mov_b32_e32 v36, v32
	v_writelane_b32 v255, s1, 21
	v_cmp_ge_u32_e64 s[0:1], v6, v15
	v_or_b32_e32 v6, 6, v135
	v_cmp_ge_u32_e64 s[50:51], v6, v15
	v_or_b32_e32 v6, 7, v135
	v_cmp_ge_u32_e64 s[52:53], v6, v15
	v_or_b32_e32 v6, 16, v135
	v_cmp_ge_u32_e64 s[2:3], v6, v15
	v_or_b32_e32 v6, 17, v135
	v_writelane_b32 v255, s0, 22
	s_and_b64 s[46:47], s[2:3], vcc
	v_cmp_ge_u32_e32 vcc, v6, v15
	v_cmp_lt_u32_e64 s[2:3], v6, v48
	v_or_b32_e32 v6, 18, v135
	v_writelane_b32 v255, s1, 23
	s_and_b64 s[0:1], vcc, s[2:3]
	v_cmp_ge_u32_e32 vcc, v6, v15
	v_cmp_lt_u32_e64 s[2:3], v6, v48
	v_or_b32_e32 v6, 19, v135
	s_and_b64 s[90:91], vcc, s[2:3]
	v_cmp_ge_u32_e32 vcc, v6, v15
	v_cmp_lt_u32_e64 s[2:3], v6, v48
	v_or_b32_e32 v6, 20, v135
	s_and_b64 s[92:93], vcc, s[2:3]
	v_cmp_ge_u32_e32 vcc, v6, v15
	v_cmp_lt_u32_e64 s[2:3], v6, v48
	v_or_b32_e32 v6, 21, v135
	s_and_b64 s[94:95], vcc, s[2:3]
	v_cmp_ge_u32_e32 vcc, v6, v15
	v_cmp_lt_u32_e64 s[2:3], v6, v48
	v_or_b32_e32 v6, 22, v135
	s_and_b64 s[26:27], vcc, s[2:3]
	v_cmp_ge_u32_e32 vcc, v6, v15
	v_cmp_lt_u32_e64 s[2:3], v6, v48
	v_or_b32_e32 v6, 23, v135
	s_and_b64 s[24:25], vcc, s[2:3]
	v_cmp_ge_u32_e32 vcc, v6, v15
	v_cmp_lt_u32_e64 s[2:3], v6, v48
	v_or_b32_e32 v6, 32, v135
	s_and_b64 s[72:73], vcc, s[2:3]
	v_cmp_ge_u32_e32 vcc, v6, v15
	v_cmp_lt_u32_e64 s[2:3], v6, v48
	v_or_b32_e32 v6, 33, v135
	s_and_b64 s[74:75], vcc, s[2:3]
	v_cmp_ge_u32_e32 vcc, v6, v15
	v_cmp_lt_u32_e64 s[2:3], v6, v48
	v_or_b32_e32 v6, 34, v135
	s_and_b64 s[76:77], vcc, s[2:3]
	v_cmp_ge_u32_e32 vcc, v6, v15
	v_cmp_lt_u32_e64 s[2:3], v6, v48
	v_or_b32_e32 v6, 35, v135
	s_and_b64 s[78:79], vcc, s[2:3]
	v_cmp_ge_u32_e32 vcc, v6, v15
	v_cmp_lt_u32_e64 s[2:3], v6, v48
	v_or_b32_e32 v6, 36, v135
	s_and_b64 s[80:81], vcc, s[2:3]
	v_cmp_ge_u32_e32 vcc, v6, v15
	v_cmp_lt_u32_e64 s[2:3], v6, v48
	v_or_b32_e32 v6, 37, v135
	s_and_b64 s[82:83], vcc, s[2:3]
	v_cmp_ge_u32_e32 vcc, v6, v15
	v_cmp_lt_u32_e64 s[2:3], v6, v48
	v_or_b32_e32 v6, 38, v135
	s_and_b64 s[84:85], vcc, s[2:3]
	v_cmp_ge_u32_e32 vcc, v6, v15
	v_cmp_lt_u32_e64 s[2:3], v6, v48
	v_or_b32_e32 v6, 39, v135
	s_and_b64 s[86:87], vcc, s[2:3]
	v_cmp_ge_u32_e32 vcc, v6, v15
	v_cmp_lt_u32_e64 s[2:3], v6, v48
	v_or_b32_e32 v6, 48, v135
	v_cmp_lt_u32_e64 s[54:55], v6, v48
	v_or_b32_e32 v6, 49, v135
	v_cmp_lt_u32_e64 s[56:57], v6, v48
	v_lshlrev_b32_e32 v6, 2, v19
	v_mov_b32_e32 v37, v32
	v_mov_b32_e32 v38, v32
	v_mov_b32_e32 v39, v32
	v_mov_b32_e32 v40, v32
	v_mov_b32_e32 v41, v32
	v_mov_b32_e32 v42, v32
	v_mov_b32_e32 v43, v32
	v_mov_b32_e32 v44, v32
	v_mov_b32_e32 v45, v32
	v_mov_b32_e32 v46, v32
	v_mov_b32_e32 v47, v32
	s_and_b64 s[2:3], vcc, s[2:3]
	v_sub_u32_e32 v132, s28, v6
	v_add_u32_e32 v139, v1, v2
	v_add_u32_e32 v140, v3, v0
	v_add_u32_e32 v141, v4, v192
	v_add_u32_e32 v142, v5, v192
	v_mov_b32_e32 v0, 0
	v_mov_b32_e32 v1, v138
	v_mov_b32_e32 v2, v138
	v_mov_b32_e32 v3, v138
	v_mov_b32_e32 v4, v138
	v_mov_b32_e32 v5, v138
	v_mov_b32_e32 v6, v138
	v_mov_b32_e32 v7, v138
	v_mov_b32_e32 v8, v138
	v_mov_b32_e32 v9, v138
	v_mov_b32_e32 v10, v138
	v_mov_b32_e32 v11, v138
	v_mov_b32_e32 v12, v138
	v_mov_b32_e32 v13, v138
	v_mov_b32_e32 v14, v138
	v_mov_b32_e32 v15, v138
	v_mov_b32_e32 v16, 0
	v_mov_b32_e32 v17, v138
	v_mov_b32_e32 v18, v138
	v_mov_b32_e32 v19, v138
	v_mov_b32_e32 v20, v138
	v_mov_b32_e32 v21, v138
	v_mov_b32_e32 v22, v138
	v_mov_b32_e32 v23, v138
	v_mov_b32_e32 v24, v138
	v_mov_b32_e32 v25, v138
	v_mov_b32_e32 v26, v138
	v_mov_b32_e32 v27, v138
	v_mov_b32_e32 v28, v138
	v_mov_b32_e32 v29, v138
	v_mov_b32_e32 v30, v138
	v_mov_b32_e32 v31, v138
	v_cmp_lt_u32_e64 s[58:59], v49, v48
	v_cmp_lt_u32_e64 s[60:61], v50, v48
	v_cmp_lt_u32_e64 s[62:63], v51, v48
	v_cmp_lt_u32_e64 s[64:65], v52, v48
	v_cmp_lt_u32_e64 s[66:67], v53, v48
	v_cmp_lt_u32_e64 s[68:69], v54, v48
	s_mov_b32 s100, 0xd000
	s_mov_b32 s101, 0
	s_branch .LBB0_339

; #define MFMA32(a, b, c) __builtin_amdgcn_mfma_f32_32x32x16_bf16((a), (b), (c), 0, 0, 0)
; DI float fexp2(float x) { return __builtin_amdgcn_exp2f(x); }
; DI void frag64_load(Frag64& f, const bf16_t* P, const bf16_t* vt, int b, int u, int kcol, int lane) {
;     ...
;     f.k[i] = *(const u32x4*)(P + (size_t)rowOfU(b, u + (lane >> 3) + 8 * i) * NP + kcol + (lane & 7) * 8);
;     f.v[i] = *(const u32x4*)(vt + (size_t)((lane >> 2) + 16 * i) * UA + u + (lane & 3) * 8);
; template <int MODE>
; DI void attn64_wave(const Params& p, int layer, int b, int hq, int qrow0, int t0, const float* rpb_lds, unsigned char* wlds) {
;     ...
;   auto compute_tile = [&](const Frag64& f, int t) {
; #pragma unroll
;     for (int i = 0; i < 4; ++i) {
;       *(u32x4*)(Kw + ((lane >> 3) + 8 * i) * LDS_STRIDE + (lane & 7) * 16) = f.k[i];
;       *(u32x4*)(Vw + ((lane >> 2) + 16 * i) * W64_VSTR + (lane & 3) * 16) = f.v[i];
;     }
;     bf16x8 kf[4], vf[2][2];
; #pragma unroll
;     for (int ks = 0; ks < 4; ++ks) kf[ks] = __builtin_bit_cast(bf16x8, *(const u32x4*)(Kw + pr * LDS_STRIDE + (16 * ks + 8 * hh) * 2));
; #pragma unroll
;     for (int dh = 0; dh < 2; ++dh)
; #pragma unroll
;       for (int s2 = 0; s2 < 2; ++s2) vf[dh][s2] = __builtin_bit_cast(bf16x8, *(const u32x4*)(Vw + (32 * dh + qi) * W64_VSTR + (16 * s2 + 8 * hh) * 2));
;     f32x16 s;
; #pragma unroll
;     for (int i = 0; i < 16; ++i) s[i] = negM2;
; #pragma unroll
;     for (int ks = 0; ks < 4; ++ks) s = MFMA32(kf[ks], qf[ks], s);
;     float pe[16];
;     if (t < 8) {
; #pragma unroll
;       for (int i = 0; i < 16; ++i) pe[i] = fexp2(s[i]);
;     } else if (MODE == 0) {
;       const int kr = rs + ((t - 8) >> 1), hf = (t - 8) & 1;
;       const float* rrow = rpb + (kr - r + 7) * 31 + 15 - c;
; #pragma unroll
;       for (int i = 0; i < 16; ++i) {
;         const int kc = hf * 32 + 16 * (i >> 3) + 8 * hh + (i & 7);
;         const bool valid = (kc >= ws) && (kc < ws + 16);
;         const int kcc = min(max(kc, ws), ws + 15);
;         pe[i] = fexp2(valid ? s[i] + rrow[kcc] : -1e30f);
.LBB0_341:
	v_add_u32_e32 v126, v192, v134
	s_movk_i32 s30, 0x100
	v_mov_b32_e32 v127, s22
	v_mov_b32_e32 v143, s42
	v_cmp_gt_i32_e32 vcc, s30, v126
	v_lshl_add_u64 v[124:125], v[192:193], 1, v[130:131]
	global_load_dwordx4 v[116:119], v[124:125], off
	v_cndmask_b32_e32 v48, v127, v143, vcc
	v_add_u32_e32 v48, v48, v126
	v_mad_i64_i32 v[166:167], s[30:31], v48, s20, v[128:129]
	s_movk_i32 s30, 0xf8
	s_nop 0
	global_load_dwordx4 v[112:115], v[166:167], off
	s_nop 0
	v_lshl_add_u64 v[166:167], v[166:167], 0, s[100:101]
	global_load_dwordx4 v[120:123], v[166:167], off
	s_waitcnt vmcnt(9)
	ds_write_b128 v139, v[84:87] offset:8192
	ds_write_b128 v140, v[80:83] offset:12800
	s_waitcnt vmcnt(8)
	ds_write_b128 v139, v[88:91] offset:9344
	s_waitcnt vmcnt(7)
	ds_write_b128 v140, v[92:95] offset:14080
	s_waitcnt vmcnt(6)
	ds_write_b128 v139, v[96:99] offset:10496
	s_waitcnt vmcnt(5)
	ds_write_b128 v140, v[100:103] offset:15360
	s_waitcnt vmcnt(4)
	ds_write_b128 v139, v[104:107] offset:11648
	s_waitcnt vmcnt(3)
	ds_write_b128 v140, v[108:111] offset:16640
	ds_read_b128 v[80:83], v141 offset:8192
	ds_read_b128 v[84:87], v141 offset:8224
	v_add_co_u32_e32 v48, vcc, s89, v124
	s_movk_i32 s30, 0xf0
	s_nop 0
	v_addc_co_u32_e32 v49, vcc, 0, v125, vcc
	global_load_dwordx4 v[92:95], v[48:49], off
	ds_read_b128 v[146:149], v141 offset:8288
	v_lshl_add_u64 v[166:167], v[166:167], 0, s[100:101]
	global_load_dwordx4 v[96:99], v[166:167], off
	s_waitcnt lgkmcnt(2)
	v_mfma_f32_32x32x16_bf16 v[48:63], v[80:83], v[72:75], v[32:47]
	v_add_co_u32_e32 v80, vcc, s48, v124
	s_movk_i32 s30, 0xe8
	s_nop 0
	v_addc_co_u32_e32 v81, vcc, 0, v125, vcc
	global_load_dwordx4 v[100:103], v[80:81], off
	s_waitcnt lgkmcnt(1)
	v_mfma_f32_32x32x16_bf16 v[48:63], v[84:87], v[64:67], v[48:63]
	v_lshl_add_u64 v[166:167], v[166:167], 0, s[100:101]
	global_load_dwordx4 v[104:107], v[166:167], off
	v_add_co_u32_e32 v84, vcc, s49, v124
	ds_read_b128 v[80:83], v141 offset:8256
	s_nop 0
	v_addc_co_u32_e32 v85, vcc, 0, v125, vcc
	global_load_dwordx4 v[108:111], v[84:85], off
	s_waitcnt lgkmcnt(0)
	v_mfma_f32_32x32x16_bf16 v[48:63], v[80:83], v[68:71], v[48:63]
	ds_read_b128 v[88:91], v142 offset:12800
	ds_read_b128 v[80:83], v142 offset:12832
	ds_read_b128 v[124:127], v142 offset:15360
	ds_read_b128 v[84:87], v142 offset:15392
	s_and_b64 vcc, exec, s[28:29]
	v_mfma_f32_32x32x16_bf16 v[48:63], v[146:149], v[76:79], v[48:63]
	s_cbranch_vccz .LBB0_375
	s_add_i32 s30, s43, -8
	s_lshr_b32 s30, s30, 1
	v_add_u32_e32 v143, s30, v137
	s_movk_i32 s30, 0x7c
	v_mad_u64_u32 v[146:147], s[30:31], v143, s30, v[132:133]
	v_mov_b32_e32 v143, 0xf149f2ca
	v_lshl_add_u32 v147, v135, 2, v146
	v_mov_b32_e32 v146, 0xf149f2ca
	s_mov_b64 s[30:31], exec
	v_readlane_b32 s44, v255, 12
	v_readlane_b32 s45, v255, 13
	s_and_b64 s[44:45], s[30:31], s[44:45]
	s_mov_b64 exec, s[44:45]
	s_cbranch_execz .LBB0_344
	ds_read_b32 v146, v147 offset:928
	s_waitcnt lgkmcnt(0)
	v_add_f32_e32 v146, v48, v146

; #define MFMA32(a, b, c) __builtin_amdgcn_mfma_f32_32x32x16_bf16((a), (b), (c), 0, 0, 0)
; DI float fexp2(float x) { return __builtin_amdgcn_exp2f(x); }
; DI void frag64_load(Frag64& f, const bf16_t* P, const bf16_t* vt, int b, int u, int kcol, int lane) {
;     ...
;     f.k[i] = *(const u32x4*)(P + (size_t)rowOfU(b, u + (lane >> 3) + 8 * i) * NP + kcol + (lane & 7) * 8);
;     f.v[i] = *(const u32x4*)(vt + (size_t)((lane >> 2) + 16 * i) * UA + u + (lane & 3) * 8);
; template <int MODE>
; DI void attn64_wave(const Params& p, int layer, int b, int hq, int qrow0, int t0, const float* rpb_lds, unsigned char* wlds) {
;     ...
;   auto compute_tile = [&](const Frag64& f, int t) {
; #pragma unroll
;     for (int i = 0; i < 4; ++i) {
;       *(u32x4*)(Kw + ((lane >> 3) + 8 * i) * LDS_STRIDE + (lane & 7) * 16) = f.k[i];
;       *(u32x4*)(Vw + ((lane >> 2) + 16 * i) * W64_VSTR + (lane & 3) * 16) = f.v[i];
;     }
;     bf16x8 kf[4], vf[2][2];
; #pragma unroll
;     for (int ks = 0; ks < 4; ++ks) kf[ks] = __builtin_bit_cast(bf16x8, *(const u32x4*)(Kw + pr * LDS_STRIDE + (16 * ks + 8 * hh) * 2));
; #pragma unroll
;     for (int dh = 0; dh < 2; ++dh)
; #pragma unroll
;       for (int s2 = 0; s2 < 2; ++s2) vf[dh][s2] = __builtin_bit_cast(bf16x8, *(const u32x4*)(Vw + (32 * dh + qi) * W64_VSTR + (16 * s2 + 8 * hh) * 2));
;     f32x16 s;
; #pragma unroll
;     for (int i = 0; i < 16; ++i) s[i] = negM2;
; #pragma unroll
;     for (int ks = 0; ks < 4; ++ks) s = MFMA32(kf[ks], qf[ks], s);
;     float pe[16];
;     if (t < 8) {
; #pragma unroll
;       for (int i = 0; i < 16; ++i) pe[i] = fexp2(s[i]);
;     } else if (MODE == 0) {
;       const int kr = rs + ((t - 8) >> 1), hf = (t - 8) & 1;
;       const float* rrow = rpb + (kr - r + 7) * 31 + 15 - c;
; #pragma unroll
;       for (int i = 0; i < 16; ++i) {
;         const int kc = hf * 32 + 16 * (i >> 3) + 8 * hh + (i & 7);
;         const bool valid = (kc >= ws) && (kc < ws + 16);
;         const int kcc = min(max(kc, ws), ws + 15);
;         pe[i] = fexp2(valid ? s[i] + rrow[kcc] : -1e30f);
.LBB0_381:
	v_add_u32_e32 v126, v48, v134
	s_movk_i32 s45, 0x100
	v_mov_b32_e32 v127, s22
	v_mov_b32_e32 v143, s42
	v_cmp_gt_i32_e32 vcc, s45, v126
	s_movk_i32 s45, 0xf8
	v_ashrrev_i32_e32 v49, 31, v48
	v_cndmask_b32_e32 v50, v127, v143, vcc
	v_add_u32_e32 v50, v50, v126
	v_mad_i64_i32 v[166:167], vcc, v50, s20, v[128:129]
	v_lshl_add_u64 v[124:125], v[48:49], 1, v[130:131]
	global_load_dwordx4 v[84:87], v[166:167], off
	v_lshl_add_u64 v[166:167], v[166:167], 0, s[100:101]
	global_load_dwordx4 v[80:83], v[124:125], off
	global_load_dwordx4 v[88:91], v[166:167], off
	s_waitcnt vmcnt(9)
	ds_write_b128 v139, v[112:115] offset:8192
	ds_write_b128 v140, v[116:119] offset:12800
	s_waitcnt vmcnt(8)
	ds_write_b128 v139, v[120:123] offset:9344
	s_waitcnt vmcnt(7)
	ds_write_b128 v140, v[92:95] offset:14080
	s_waitcnt vmcnt(6)
	ds_write_b128 v139, v[96:99] offset:10496
	s_waitcnt vmcnt(5)
	ds_write_b128 v140, v[100:103] offset:15360
	s_waitcnt vmcnt(4)
	ds_write_b128 v139, v[104:107] offset:11648
	s_waitcnt vmcnt(3)
	ds_write_b128 v140, v[108:111] offset:16640
	ds_read_b128 v[100:103], v141 offset:8192
	ds_read_b128 v[104:107], v141 offset:8224
	v_add_co_u32_e32 v48, vcc, s89, v124
	s_movk_i32 s45, 0xf0
	s_nop 0
	v_addc_co_u32_e32 v49, vcc, 0, v125, vcc
	global_load_dwordx4 v[92:95], v[48:49], off
	s_movk_i32 s45, 0xe8
	v_lshl_add_u64 v[166:167], v[166:167], 0, s[100:101]
	global_load_dwordx4 v[96:99], v[166:167], off
	s_waitcnt lgkmcnt(1)
	v_mfma_f32_32x32x16_bf16 v[48:63], v[100:103], v[72:75], v[32:47]
	v_add_co_u32_e32 v100, vcc, s48, v124
	ds_read_b128 v[146:149], v141 offset:8288
	s_nop 0
	v_addc_co_u32_e32 v101, vcc, 0, v125, vcc
	global_load_dwordx4 v[100:103], v[100:101], off
	s_waitcnt lgkmcnt(1)
	v_mfma_f32_32x32x16_bf16 v[48:63], v[104:107], v[64:67], v[48:63]
	ds_read_b128 v[108:111], v141 offset:8256
	v_lshl_add_u64 v[166:167], v[166:167], 0, s[100:101]
	v_add_co_u32_e32 v112, vcc, s49, v124
	global_load_dwordx4 v[104:107], v[166:167], off
	s_nop 0
	v_addc_co_u32_e32 v113, vcc, 0, v125, vcc
	s_waitcnt lgkmcnt(0)
	v_mfma_f32_32x32x16_bf16 v[48:63], v[108:111], v[68:71], v[48:63]
	global_load_dwordx4 v[108:111], v[112:113], off
	ds_read_b128 v[120:123], v142 offset:12800
	ds_read_b128 v[112:115], v142 offset:12832
	ds_read_b128 v[124:127], v142 offset:15360
	ds_read_b128 v[116:119], v142 offset:15392
	s_and_b64 vcc, exec, s[28:29]
	v_mfma_f32_32x32x16_bf16 v[48:63], v[146:149], v[76:79], v[48:63]
	s_cbranch_vccz .LBB0_415
	s_add_i32 s28, s43, -7
	s_lshr_b32 s28, s28, 1
	v_add_u32_e32 v143, s28, v137
	s_movk_i32 s28, 0x7c
	v_mad_u64_u32 v[146:147], s[28:29], v143, s28, v[132:133]
	v_mov_b32_e32 v143, 0xf149f2ca
	v_lshl_add_u32 v147, v135, 2, v146
	v_mov_b32_e32 v146, 0xf149f2ca
	s_and_saveexec_b64 s[28:29], s[74:75]
	s_cbranch_execz .LBB0_384
	ds_read_b32 v146, v147 offset:1056
	s_waitcnt lgkmcnt(0)
	v_add_f32_e32 v146, v48, v146

; DI int ltid() { int t = threadIdx.x & 255; asm volatile("" : "+v"(t)); return t; }
; template <int MODE>
; DI void attn64_wave(const Params& p, int layer, int b, int hq, int qrow0, int t0, const float* rpb_lds, unsigned char* wlds) {
;   constexpr bool isC = (MODE == 0 || MODE == 2);
;   const int lane = ltid() & 63, qi = lane & 31, hh = lane >> 5;
;   const int pr = (qi & 19) | ((qi & 4) << 1) | ((qi & 8) >> 1);
;   const float* gqp = (isC ? p.na_q_gain : p.sw_q_gain) + layer * 64;
;   const float* gkp = (isC ? p.na_k_gain : p.sw_k_gain) + layer * 64;
;   const float gq = wave_max(fabsf(gqp[lane])), gk = wave_max(fabsf(gkp[lane]));
;   const float negM2 = -(0.125f * LOG2E * 64.f * 1.02f) * gq * gk;
;   const int kvh = isC ? hq : (hq >> 1);
;   const int qcol = isC ? 2048 + 64 * hq : 2816 + 64 * hq;
;   const int kcol = isC ? 2304 + 64 * hq : 3072 + 64 * kvh;
;   const bf16_t* vt = isC ? p.VtC + (size_t)(b * 4 + hq) * 64 * UA : p.VtD + (size_t)(b * 2 + kvh) * 64 * UA;
;   const bf16_t* qp = p.P + (size_t)(qrow0 + qi) * NP + qcol + 8 * hh;
;   bf16x8 qf[4];
; #pragma unroll
;   for (int ks = 0; ks < 4; ++ks) qf[ks] = *(const bf16x8*)(qp + ks * 16);
;   f32x16 o[2];
; #pragma unroll
;   for (int dh = 0; dh < 2; ++dh)
; #pragma unroll
;     for (int i = 0; i < 16; ++i) o[dh][i] = 0.f;
;   float ls = 0.f;
;   constexpr int NT = MODE == 0 ? 24 : (MODE == 1 ? 18 : 8);
;   const int r = t0 >> 6, c = (t0 & 63) + qi;
;   const int rs = min(max(r - 4, 0), 248), ws = min(max(c - 8, 0), 48);
.LBB0_419:
	s_nop 2
	v_mov_b32_e32 v10, v212
	v_readlane_b32 s2, v255, 4
	v_and_b32_e32 v4, 63, v10
	v_lshlrev_b32_e32 v0, 2, v4
	v_readlane_b32 s3, v255, 5
	v_readlane_b32 s24, v255, 6
	v_readlane_b32 s25, v255, 7
	v_cmp_lt_i32_e32 vcc, v218, v217
	v_lshlrev_b32_e32 v23, 4, v4
	v_mov_b32_e32 v5, v193
	global_load_dword v11, v0, s[2:3]
	v_cndmask_b32_e32 v2, v216, v218, vcc
	global_load_dword v12, v0, s[24:25]
	s_and_b32 s2, s38, 0x3f80
	s_sub_i32 s3, s40, s27
	v_add_u32_e32 v132, s2, v152
	s_lshr_b32 s2, s3, 7
	s_ashr_i32 s27, s3, 9
	v_cmp_lt_i32_e32 vcc, v219, v217
	s_bfe_u32 s26, s3, 0x20007
	s_lshl_b32 s3, s3, 7
	s_bfe_u32 s29, s2, 0x10001
	s_lshl_b32 s2, s27, 1
	v_cndmask_b32_e32 v6, v216, v219, vcc
	v_cmp_lt_i32_e32 vcc, v220, v217
	s_and_b32 s3, s3, 0x3f80
	s_lshl_b32 s22, s26, 6
	s_or_b32 s2, s29, s2
	v_cndmask_b32_e32 v8, v216, v220, vcc
	s_lshl_b32 s28, s27, 14
	v_add_u32_e32 v20, s3, v152
	s_mov_b64 s[44:45], s[22:23]
	s_lshl_b32 s22, s26, 7
	s_mul_hi_i32 s3, s2, 0x208000
	s_mul_i32 s2, s2, 0x208000
	v_cmp_lt_i32_e32 vcc, v221, v217
	v_lshlrev_b32_e32 v133, 2, v2
	v_lshlrev_b32_e32 v16, 2, v8
	v_lshlrev_b32_e32 v2, 1, v10
	v_lshlrev_b32_e32 v8, 4, v10
	s_add_u32 s2, s86, s2
	v_cndmask_b32_e32 v9, v216, v221, vcc
	v_and_b32_e32 v18, 31, v10
	v_and_b32_e32 v21, 8, v2
	v_and_b32_e32 v2, 0x70, v8
	v_add_u32_e32 v8, s28, v20
	v_and_b32_e32 v4, 48, v23
	s_addc_u32 s3, s87, s3
	v_mov_b64_e32 v[0:1], s[78:79]
	v_lshlrev_b32_e32 v17, 2, v9
	v_or_b32_e32 v144, v18, v8
	v_lshl_add_u64 v[8:9], s[2:3], 0, v[4:5]
	v_bfe_u32 v155, v10, 5, 1
	v_mad_i64_i32 v[0:1], s[24:25], v144, s20, v[0:1]
	v_cmp_lt_i32_e32 vcc, v222, v217
	v_lshlrev_b32_e32 v15, 2, v6
	v_lshrrev_b32_e32 v6, 1, v10
	v_bfe_u32 v19, v10, 2, 4
	v_lshlrev_b32_e32 v192, 4, v155
	v_lshl_add_u64 v[0:1], v[0:1], 0, s[22:23]
	v_cndmask_b32_e32 v13, v216, v222, vcc
	v_cmp_lt_i32_e32 vcc, v223, v217
	v_mov_b32_e32 v7, v193
	v_and_b32_e32 v22, 4, v6
	v_mul_u32_u24_e32 v6, 0x8200, v19
	v_lshl_add_u64 v[0:1], v[0:1], 0, v[192:193]
	s_mov_b64 s[2:3], 0x1600
	v_cndmask_b32_e32 v14, v216, v223, vcc
	v_lshl_add_u64 v[128:129], v[8:9], 0, v[6:7]
	v_lshl_add_u64 v[6:7], v[0:1], 0, s[2:3]
	v_add_co_u32_e32 v0, vcc, s63, v0
	global_load_dwordx4 v[80:83], v[128:129], off
	s_nop 0
	v_addc_co_u32_e32 v1, vcc, 0, v1, vcc
	global_load_dwordx4 v[64:67], v[6:7], off offset:32
	global_load_dwordx4 v[68:71], v[6:7], off offset:64
	global_load_dwordx4 v[72:75], v[0:1], off offset:1536
	global_load_dwordx4 v[76:79], v[6:7], off offset:96
	s_lshl_b32 s24, s29, 7
	s_add_u32 s24, s78, s24
	v_mov_b32_e32 v3, v193
	s_addc_u32 s25, s79, 0
	v_lshl_add_u64 v[2:3], s[24:25], 0, v[2:3]
	s_mov_b64 s[2:3], 0x1800
	v_lshl_add_u64 v[130:131], v[2:3], 0, s[2:3]
	v_lshlrev_b32_e32 v13, 2, v13
	s_lshl_b32 s22, s27, 8
	v_bfe_u32 v134, v10, 3, 3
	s_add_i32 s22, s22, 0x8000
	v_lshlrev_b32_e32 v14, 2, v14
	v_mov_b32_e32 v135, 0
	s_waitcnt vmcnt(6)
	v_and_b32_e32 v5, 0x7fffffff, v11
	ds_bpermute_b32 v5, v133, v5
	v_max_f32_e64 v0, |v11|, |v11|
	s_waitcnt vmcnt(5)
	v_and_b32_e32 v2, 0x7fffffff, v12
	ds_bpermute_b32 v2, v133, v2
	v_max_f32_e64 v3, |v12|, |v12|
	s_waitcnt lgkmcnt(1)
	v_max_f32_e32 v1, v5, v5
	v_max_f32_e32 v0, v0, v1
	ds_bpermute_b32 v1, v15, v0
	s_waitcnt lgkmcnt(1)
	v_max_f32_e32 v2, v2, v2
	v_max_f32_e32 v2, v3, v2
	ds_bpermute_b32 v3, v15, v2
	v_or_b32_e32 v5, s22, v134
	s_waitcnt lgkmcnt(1)
	v_max_f32_e32 v1, v1, v1
	v_max_f32_e32 v0, v0, v1
	ds_bpermute_b32 v1, v16, v0
	s_waitcnt lgkmcnt(1)
	v_max_f32_e32 v3, v3, v3
	v_max_f32_e32 v2, v2, v3
	ds_bpermute_b32 v3, v16, v2
	v_or_b32_e32 v8, 8, v5
	s_waitcnt lgkmcnt(1)
; template <int MODE>
; DI void attn64_wave(const Params& p, int layer, int b, int hq, int qrow0, int t0, const float* rpb_lds, unsigned char* wlds) {
;     ...
;   const float gq = wave_max(fabsf(gqp[lane])), gk = wave_max(fabsf(gkp[lane]));
;   const float negM2 = -(0.125f * LOG2E * 64.f * 1.02f) * gq * gk;
;   const int kvh = isC ? hq : (hq >> 1);
;   const int qcol = isC ? 2048 + 64 * hq : 2816 + 64 * hq;
;   const int kcol = isC ? 2304 + 64 * hq : 3072 + 64 * kvh;
;   const bf16_t* vt = isC ? p.VtC + (size_t)(b * 4 + hq) * 64 * UA : p.VtD + (size_t)(b * 2 + kvh) * 64 * UA;
;   const bf16_t* qp = p.P + (size_t)(qrow0 + qi) * NP + qcol + 8 * hh;
;   bf16x8 qf[4];
; #pragma unroll
;   for (int ks = 0; ks < 4; ++ks) qf[ks] = *(const bf16x8*)(qp + ks * 16);
;   f32x16 o[2];
; #pragma unroll
;   for (int dh = 0; dh < 2; ++dh)
; #pragma unroll
;     for (int i = 0; i < 16; ++i) o[dh][i] = 0.f;
;   float ls = 0.f;
;   constexpr int NT = MODE == 0 ? 24 : (MODE == 1 ? 18 : 8);
;   const int r = t0 >> 6, c = (t0 & 63) + qi;
;   const int rs = min(max(r - 4, 0), 248), ws = min(max(c - 8, 0), 48);
;   const float* rpb = rpb_lds + hq * 465;
;   const int qt = t0 + qi;
	v_max_f32_e32 v1, v1, v1
	v_max_f32_e32 v6, v0, v1
	ds_bpermute_b32 v7, v17, v6
	s_waitcnt lgkmcnt(1)
	v_max_f32_e32 v3, v3, v3
	v_mad_u64_u32 v[0:1], s[2:3], v5, s20, v[130:131]
	v_max_f32_e32 v9, v2, v3
	s_waitcnt lgkmcnt(0)
	v_max_f32_e32 v7, v7, v7
	v_max_f32_e32 v6, v6, v7
	ds_bpermute_b32 v7, v13, v6
	ds_bpermute_b32 v11, v17, v9
	s_mov_b32 s29, 0
	s_mov_b32 s27, 32
	v_ashrrev_i32_e32 v145, 31, v144
	s_waitcnt lgkmcnt(1)
	v_max_f32_e32 v2, v7, v7
	v_max_f32_e32 v6, v6, v2
	v_mad_u64_u32 v[2:3], s[2:3], v8, s20, v[130:131]
	global_load_dwordx4 v[84:87], v[0:1], off
	global_load_dwordx4 v[88:91], v[2:3], off
	v_add_co_u32_e32 v0, vcc, s61, v128
	v_lshlrev_b32_e32 v3, 3, v155
	s_nop 0
	v_addc_co_u32_e32 v1, vcc, 0, v129, vcc
	global_load_dwordx4 v[92:95], v[0:1], off
	v_or_b32_e32 v0, 16, v5
	v_mad_u64_u32 v[0:1], s[2:3], v0, s20, v[130:131]
	global_load_dwordx4 v[96:99], v[0:1], off
	v_add_co_u32_e32 v0, vcc, s62, v128
	s_addk_i32 s28, 0xff00
	s_nop 0
	v_addc_co_u32_e32 v1, vcc, 0, v129, vcc
	global_load_dwordx4 v[100:103], v[0:1], off
	v_or_b32_e32 v0, 24, v5
	v_mad_u64_u32 v[0:1], s[2:3], v0, s20, v[130:131]
	global_load_dwordx4 v[104:107], v[0:1], off
	v_add_co_u32_e32 v0, vcc, 0x186000, v128
	v_and_b32_e32 v5, 19, v10
	s_nop 0
	v_addc_co_u32_e32 v1, vcc, 0, v129, vcc
	global_load_dwordx4 v[108:111], v[0:1], off
	s_waitcnt lgkmcnt(0)
	v_max_f32_e32 v1, v11, v11
	v_max_f32_e32 v1, v9, v1
	ds_bpermute_b32 v2, v13, v1
	ds_bpermute_b32 v0, v14, v6
	v_add_u32_e32 v136, 0xfffffe80, v20
	v_sub_u32_e32 v137, v3, v18
	v_mov_b32_e32 v3, v135
	s_waitcnt lgkmcnt(1)
	v_max_f32_e32 v2, v2, v2
	v_max_f32_e32 v1, v1, v2
	ds_bpermute_b32 v2, v14, v1
	s_waitcnt lgkmcnt(1)
	v_max_f32_e32 v0, v0, v0
	v_max_f32_e32 v0, v6, v0
	v_mul_f32_e32 v0, 0xc13c5bb7, v0
	v_mad_u32_u24 v6, v18, s60, v153
	s_waitcnt lgkmcnt(0)
	v_max_f32_e32 v2, v2, v2
	v_max_f32_e32 v1, v1, v2
	v_or3_b32 v2, v5, v21, v22
	v_mul_f32_e32 v32, v0, v1
	v_mad_u32_u24 v0, v134, s59, v153
	v_and_b32_e32 v1, 0x70, v23
	v_mad_u32_u24 v5, v19, s60, v153
	v_mad_u32_u24 v2, v2, s59, v153
	v_mov_b32_e32 v33, v32
	v_mov_b32_e32 v34, v32
	v_mov_b32_e32 v35, v32
	v_mov_b32_e32 v36, v32
	v_mov_b32_e32 v37, v32
	v_mov_b32_e32 v38, v32
	v_mov_b32_e32 v39, v32
	v_mov_b32_e32 v40, v32
	v_mov_b32_e32 v41, v32
	v_mov_b32_e32 v42, v32
	v_mov_b32_e32 v43, v32
	v_mov_b32_e32 v44, v32
	v_mov_b32_e32 v45, v32
	v_mov_b32_e32 v46, v32
	v_mov_b32_e32 v47, v32
	v_add_u32_e32 v138, v0, v1
	v_add_u32_e32 v139, v5, v4
	v_add_u32_e32 v140, v2, v192
	v_add_u32_e32 v141, v6, v192
	v_mov_b32_e32 v0, 0
	v_mov_b32_e32 v1, v135
	v_mov_b32_e32 v2, v135
	v_mov_b32_e32 v4, v135
	v_mov_b32_e32 v5, v135
	v_mov_b32_e32 v6, v135
	v_mov_b32_e32 v7, v135
	v_mov_b32_e32 v8, v135
	v_mov_b32_e32 v9, v135
	v_mov_b32_e32 v10, v135
	v_mov_b32_e32 v11, v135
	v_mov_b32_e32 v12, v135
	v_mov_b32_e32 v13, v135
	v_mov_b32_e32 v14, v135
	v_mov_b32_e32 v15, v135
	v_mov_b32_e32 v16, 0
	v_mov_b32_e32 v17, v135
	v_mov_b32_e32 v18, v135
	v_mov_b32_e32 v19, v135
	v_mov_b32_e32 v20, v135
	v_mov_b32_e32 v21, v135
	v_mov_b32_e32 v22, v135
	v_mov_b32_e32 v23, v135
	v_mov_b32_e32 v24, v135
	v_mov_b32_e32 v25, v135
	v_mov_b32_e32 v26, v135
	v_mov_b32_e32 v27, v135
	v_mov_b32_e32 v28, v135
	v_mov_b32_e32 v29, v135
	v_mov_b32_e32 v30, v135
	v_mov_b32_e32 v31, v135
	v_readfirstlane_b32 s98, v132
	s_add_i32 s98, s98, 0xffffff80
	s_cmp_lt_u32 s98, 0x3ee1
	s_cselect_b64 s[98:99], -1, 0
	s_mov_b32 s46, 0xd000
	s_mov_b32 s47, 0
	s_branch .LBB0_421

; DI void frag64_load(Frag64& f, const bf16_t* P, const bf16_t* vt, int b, int u, int kcol, int lane) {
;     ...
;     f.k[i] = *(const u32x4*)(P + (size_t)rowOfU(b, u + (lane >> 3) + 8 * i) * NP + kcol + (lane & 7) * 8);
;     f.v[i] = *(const u32x4*)(vt + (size_t)((lane >> 2) + 16 * i) * UA + u + (lane & 3) * 8);
; template <int MODE>
; DI void attn64_wave(const Params& p, int layer, int b, int hq, int qrow0, int t0, const float* rpb_lds, unsigned char* wlds) {
;     ...
;   auto tile_u = [&](int t) -> int {
;     if (t < 8) return 32 * t;
;     if (MODE == 0) return CTX + (rs + ((t - 8) >> 1)) * 64 + ((t - 8) & 1) * 32;
;     const int kt0 = t0 - 128 + 32 * (t - 8);
;     return CTX + min(max(kt0, 0), SEQ - 32);
;   };
;   auto load_tile = [&](Frag64& f, int t) { frag64_load(f, p.P, vt, b, tile_u(t), kcol, lane); };
;   unsigned char* Kw = wlds; unsigned char* Vw = wlds + W64_KB;
;   auto compute_tile = [&](const Frag64& f, int t) {
; #pragma unroll
;     for (int i = 0; i < 4; ++i) {
;       *(u32x4*)(Kw + ((lane >> 3) + 8 * i) * LDS_STRIDE + (lane & 7) * 16) = f.k[i];
;       *(u32x4*)(Vw + ((lane >> 2) + 16 * i) * W64_VSTR + (lane & 3) * 16) = f.v[i];
;     }
;     bf16x8 kf[4], vf[2][2];
; #pragma unroll
;     for (int ks = 0; ks < 4; ++ks) kf[ks] = __builtin_bit_cast(bf16x8, *(const u32x4*)(Kw + pr * LDS_STRIDE + (16 * ks + 8 * hh) * 2));
; #pragma unroll
;     for (int dh = 0; dh < 2; ++dh)
; #pragma unroll
;       for (int s2 = 0; s2 < 2; ++s2) vf[dh][s2] = __builtin_bit_cast(bf16x8, *(const u32x4*)(Vw + (32 * dh + qi) * W64_VSTR + (16 * s2 + 8 * hh) * 2));
;     f32x16 s;
; #pragma unroll
;     for (int i = 0; i < 16; ++i) s[i] = negM2;
; #pragma unroll
;     for (int ks = 0; ks < 4; ++ks) s = MFMA32(kf[ks], qf[ks], s);
;     float pe[16];
;     if (t < 8) {
; #pragma unroll
;       for (int i = 0; i < 16; ++i) pe[i] = fexp2(s[i]);
;     } else if (MODE == 0) {
;       const int kr = rs + ((t - 8) >> 1), hf = (t - 8) & 1;
;       const float* rrow = rpb + (kr - r + 7) * 31 + 15 - c;
; #pragma unroll
;       for (int i = 0; i < 16; ++i) {
;         const int kc = hf * 32 + 16 * (i >> 3) + 8 * hh + (i & 7);
;         const bool valid = (kc >= ws) && (kc < ws + 16);
;         const int kcc = min(max(kc, ws), ws + 15);
;         pe[i] = fexp2(valid ? s[i] + rrow[kcc] : -1e30f);
;       }
;     } else {
;       const int jt = t - 8, kt0 = t0 - 128 + 32 * jt;
.LBB0_421:
	v_add_u32_e32 v146, s27, v132
	s_cmp_gt_u32 s29, 7
	v_add_u32_e32 v142, 0xfffffe80, v146
	s_cselect_b64 s[24:25], -1, 0
	s_cmp_lt_u32 s29, 8
	v_med3_i32 v48, v142, 0, v236
	v_add_u32_e32 v48, 0x100, v48
	v_mov_b32_e32 v49, s27
	s_cselect_b64 vcc, -1, 0
	v_cndmask_b32_e32 v192, v48, v49, vcc
	v_add_u32_e32 v126, v192, v134
	s_movk_i32 s2, 0x100
	v_mov_b32_e32 v127, s28
	v_mov_b32_e32 v143, s22
	v_cmp_gt_u32_e32 vcc, s2, v126
	v_lshl_add_u64 v[124:125], v[192:193], 1, v[128:129]
	global_load_dwordx4 v[116:119], v[124:125], off
	v_cndmask_b32_e32 v48, v127, v143, vcc
	v_add_u32_e32 v48, v48, v126
	v_mad_i64_i32 v[166:167], s[2:3], v48, s20, v[130:131]
	s_movk_i32 s2, 0xf8
	s_nop 0
	global_load_dwordx4 v[112:115], v[166:167], off
	s_nop 0
	v_lshl_add_u64 v[166:167], v[166:167], 0, s[46:47]
	global_load_dwordx4 v[120:123], v[166:167], off
	s_waitcnt vmcnt(9)
	ds_write_b128 v138, v[84:87] offset:8192
	s_waitcnt vmcnt(8)
	ds_write_b128 v139, v[80:83] offset:12800
	s_waitcnt vmcnt(8)
	ds_write_b128 v138, v[88:91] offset:9344
	s_waitcnt vmcnt(7)
	ds_write_b128 v139, v[92:95] offset:14080
	s_waitcnt vmcnt(6)
	ds_write_b128 v138, v[96:99] offset:10496
	s_waitcnt vmcnt(5)
	ds_write_b128 v139, v[100:103] offset:15360
	s_waitcnt vmcnt(4)
	ds_write_b128 v138, v[104:107] offset:11648
	s_waitcnt vmcnt(3)
	ds_write_b128 v139, v[108:111] offset:16640
	ds_read_b128 v[80:83], v140 offset:8192
	ds_read_b128 v[84:87], v140 offset:8224
	v_add_co_u32_e32 v48, vcc, s61, v124
	s_movk_i32 s2, 0xf0
	s_nop 0
	v_addc_co_u32_e32 v49, vcc, 0, v125, vcc
	global_load_dwordx4 v[92:95], v[48:49], off
	ds_read_b128 v[148:151], v140 offset:8288
	v_lshl_add_u64 v[166:167], v[166:167], 0, s[46:47]
	global_load_dwordx4 v[96:99], v[166:167], off
	s_waitcnt lgkmcnt(2)
	v_mfma_f32_32x32x16_bf16 v[48:63], v[80:83], v[72:75], v[32:47]
	v_add_co_u32_e32 v80, vcc, s62, v124
	s_movk_i32 s2, 0xe8
	s_nop 0
	v_addc_co_u32_e32 v81, vcc, 0, v125, vcc
	global_load_dwordx4 v[100:103], v[80:81], off
	s_waitcnt lgkmcnt(1)
	v_mfma_f32_32x32x16_bf16 v[48:63], v[84:87], v[64:67], v[48:63]
	v_lshl_add_u64 v[166:167], v[166:167], 0, s[46:47]
	global_load_dwordx4 v[104:107], v[166:167], off
	v_add_co_u32_e32 v84, vcc, s64, v124
	ds_read_b128 v[80:83], v140 offset:8256
	s_nop 0
	v_addc_co_u32_e32 v85, vcc, 0, v125, vcc
	global_load_dwordx4 v[108:111], v[84:85], off
	s_waitcnt lgkmcnt(0)
	v_mfma_f32_32x32x16_bf16 v[48:63], v[80:83], v[68:71], v[48:63]
	ds_read_b128 v[124:127], v141 offset:12800
	ds_read_b128 v[84:87], v141 offset:12832
	ds_read_b128 v[88:91], v141 offset:15360
	ds_read_b128 v[80:83], v141 offset:15392
	s_sub_u32 s100, s29, 10
	s_cmp_lt_u32 s100, 5
	s_cselect_b64 s[100:101], s[98:99], 0
	s_andn2_b64 s[100:101], s[24:25], s[100:101]
	s_and_b64 vcc, exec, s[100:101]
	v_add_u32_e32 v143, s27, v137
	v_mfma_f32_32x32x16_bf16 v[48:63], v[148:151], v[76:79], v[48:63]
	s_cbranch_vccz .LBB0_423
	v_add_u32_e32 v146, 0xfffffe60, v146
	s_movk_i32 s2, 0x4000
	v_cmp_gt_u32_e32 vcc, s2, v146
	v_add_u32_e32 v146, 0xfffffee0, v143
	s_movk_i32 s30, 0x101
	v_cmp_gt_u32_e64 s[2:3], s30, v146
	s_and_b64 s[2:3], vcc, s[2:3]
	v_add_u32_e32 v147, 0xfffffee1, v143
	s_nop 2
	v_cndmask_b32_e64 v146, v237, v48, s[2:3]
	v_cmp_gt_u32_e64 s[2:3], s30, v147
	s_and_b64 s[2:3], vcc, s[2:3]
	v_add_u32_e32 v148, 0xfffffee2, v143
	v_cndmask_b32_e64 v147, v237, v49, s[2:3]
	v_cmp_gt_u32_e64 s[2:3], s30, v148
	s_and_b64 s[2:3], vcc, s[2:3]
	v_add_u32_e32 v149, 0xfffffee3, v143
	v_cndmask_b32_e64 v148, v237, v50, s[2:3]
	v_cmp_gt_u32_e64 s[2:3], s30, v149
	s_and_b64 s[2:3], vcc, s[2:3]
	v_add_u32_e32 v150, 0xfffffee4, v143
	v_cndmask_b32_e64 v149, v237, v51, s[2:3]
	v_cmp_gt_u32_e64 s[2:3], s30, v150
	s_and_b64 s[2:3], vcc, s[2:3]
	v_add_u32_e32 v151, 0xfffffee5, v143
	v_cndmask_b32_e64 v150, v237, v52, s[2:3]
	v_cmp_gt_u32_e64 s[2:3], s30, v151
	s_and_b64 s[2:3], vcc, s[2:3]
	v_add_u32_e32 v156, 0xfffffee6, v143
	v_cndmask_b32_e64 v151, v237, v53, s[2:3]
	v_cmp_gt_u32_e64 s[2:3], s30, v156
	s_and_b64 s[2:3], vcc, s[2:3]
	v_add_u32_e32 v157, 0xfffffee7, v143
	v_cndmask_b32_e64 v156, v237, v54, s[2:3]
	v_cmp_gt_u32_e64 s[2:3], s30, v157
	s_and_b64 s[2:3], vcc, s[2:3]
	v_add_u32_e32 v158, 0xfffffef0, v143
	v_cndmask_b32_e64 v157, v237, v55, s[2:3]
	v_cmp_gt_u32_e64 s[2:3], s30, v158
	s_and_b64 s[2:3], vcc, s[2:3]
	v_add_u32_e32 v159, 0xfffffef1, v143
	v_cndmask_b32_e64 v158, v237, v56, s[2:3]
	v_cmp_gt_u32_e64 s[2:3], s30, v159
	s_and_b64 s[2:3], vcc, s[2:3]
	v_add_u32_e32 v160, 0xfffffef2, v143
	v_cndmask_b32_e64 v159, v237, v57, s[2:3]
	v_cmp_gt_u32_e64 s[2:3], s30, v160
	s_and_b64 s[2:3], vcc, s[2:3]
	v_add_u32_e32 v161, 0xfffffef3, v143
	v_cndmask_b32_e64 v160, v237, v58, s[2:3]
	v_cmp_gt_u32_e64 s[2:3], s30, v161
	s_and_b64 s[2:3], vcc, s[2:3]
	v_add_u32_e32 v162, 0xfffffef4, v143
	v_cndmask_b32_e64 v161, v237, v59, s[2:3]
	v_cmp_gt_u32_e64 s[2:3], s30, v162
	s_and_b64 s[2:3], vcc, s[2:3]
	v_add_u32_e32 v163, 0xfffffef5, v143
	v_cndmask_b32_e64 v162, v237, v60, s[2:3]
	v_cmp_gt_u32_e64 s[2:3], s30, v163
	s_and_b64 s[2:3], vcc, s[2:3]
	v_add_u32_e32 v164, 0xfffffef6, v143
	v_cndmask_b32_e64 v163, v237, v61, s[2:3]
	v_cmp_gt_u32_e64 s[2:3], s30, v164
	s_and_b64 s[2:3], vcc, s[2:3]
	v_add_u32_e32 v165, 0xfffffef7, v143
	v_cndmask_b32_e64 v164, v237, v62, s[2:3]
	v_cmp_gt_u32_e64 s[2:3], s30, v165
	s_and_b64 vcc, vcc, s[2:3]
	v_exp_f32_e32 v146, v146
	v_exp_f32_e32 v147, v147
	v_exp_f32_e32 v148, v148
	v_exp_f32_e32 v149, v149
	v_exp_f32_e32 v150, v150
	v_exp_f32_e32 v151, v151
	v_exp_f32_e32 v156, v156
	v_exp_f32_e32 v157, v157
	v_exp_f32_e32 v158, v158
	v_exp_f32_e32 v159, v159
	v_exp_f32_e32 v160, v160
	v_exp_f32_e32 v161, v161
	v_exp_f32_e32 v162, v162
	v_exp_f32_e32 v163, v163
	v_exp_f32_e32 v164, v164
	v_cndmask_b32_e32 v63, v237, v63, vcc
	s_cbranch_execz .LBB0_424
	s_branch .LBB0_425

; DI void frag64_load(Frag64& f, const bf16_t* P, const bf16_t* vt, int b, int u, int kcol, int lane) {
; #pragma unroll
;   for (int i = 0; i < 4; ++i) {
;     f.k[i] = *(const u32x4*)(P + (size_t)rowOfU(b, u + (lane >> 3) + 8 * i) * NP + kcol + (lane & 7) * 8);
;     f.v[i] = *(const u32x4*)(vt + (size_t)((lane >> 2) + 16 * i) * UA + u + (lane & 3) * 8);
;   }
; }
; template <int MODE>
; DI void attn64_wave(const Params& p, int layer, int b, int hq, int qrow0, int t0, const float* rpb_lds, unsigned char* wlds) {
;     ...
;   auto compute_tile = [&](const Frag64& f, int t) {
; #pragma unroll
;     for (int i = 0; i < 4; ++i) {
;       *(u32x4*)(Kw + ((lane >> 3) + 8 * i) * LDS_STRIDE + (lane & 7) * 16) = f.k[i];
;       *(u32x4*)(Vw + ((lane >> 2) + 16 * i) * W64_VSTR + (lane & 3) * 16) = f.v[i];
;     }
;     bf16x8 kf[4], vf[2][2];
; #pragma unroll
;     for (int ks = 0; ks < 4; ++ks) kf[ks] = __builtin_bit_cast(bf16x8, *(const u32x4*)(Kw + pr * LDS_STRIDE + (16 * ks + 8 * hh) * 2));
; #pragma unroll
;     for (int dh = 0; dh < 2; ++dh)
; #pragma unroll
;       for (int s2 = 0; s2 < 2; ++s2) vf[dh][s2] = __builtin_bit_cast(bf16x8, *(const u32x4*)(Vw + (32 * dh + qi) * W64_VSTR + (16 * s2 + 8 * hh) * 2));
;     f32x16 s;
; #pragma unroll
;     for (int i = 0; i < 16; ++i) s[i] = negM2;
; #pragma unroll
;     for (int ks = 0; ks < 4; ++ks) s = MFMA32(kf[ks], qf[ks], s);
;     float pe[16];
;     if (t < 8) {
; #pragma unroll
;       for (int i = 0; i < 16; ++i) pe[i] = fexp2(s[i]);
;     } else if (MODE == 0) {
;       const int kr = rs + ((t - 8) >> 1), hf = (t - 8) & 1;
;       const float* rrow = rpb + (kr - r + 7) * 31 + 15 - c;
; #pragma unroll
;       for (int i = 0; i < 16; ++i) {
;         const int kc = hf * 32 + 16 * (i >> 3) + 8 * hh + (i & 7);
;         const bool valid = (kc >= ws) && (kc < ws + 16);
;         const int kcc = min(max(kc, ws), ws + 15);
;         pe[i] = fexp2(valid ? s[i] + rrow[kcc] : -1e30f);
;       }
;     } else {
;       const int jt = t - 8, kt0 = t0 - 128 + 32 * jt;
;       const bool tile_ok = (jt < 9) && (kt0 >= 0) && (kt0 < SEQ);
; #pragma unroll
;       for (int i = 0; i < 16; ++i) {
;         const int dd = kt0 + 16 * (i >> 3) + 8 * hh + (i & 7) - qt;
;         pe[i] = fexp2((tile_ok && dd <= 128 && dd >= -128) ? s[i] : -1e30f);
;       }
;     }
;     sum16_nopk(ls, pe);
; #pragma unroll
.LBB0_425:
	s_add_i32 s30, s29, 2
	s_cmp_gt_u32 s29, 15
	s_cselect_b64 s[2:3], -1, 0
	s_cmp_lt_u32 s29, 16
	s_cselect_b32 s31, s30, 0
	s_cmp_lt_u32 s31, 8
	v_cvt_pk_bf16_f32 v48, v146, v147
	v_cvt_pk_bf16_f32 v49, v148, v149
	v_cvt_pk_bf16_f32 v50, v150, v151
	v_cvt_pk_bf16_f32 v51, v156, v157
	s_cselect_b64 vcc, -1, 0
	s_lshl_b32 s31, s31, 5
	s_waitcnt lgkmcnt(3)
	v_mfma_f32_32x32x16_bf16 v[16:31], v[124:127], v[48:51], v[16:31]
	v_exp_f32_e32 v55, v63
	s_nop 0
	v_add_f32 v135, v146, v135
	v_add_f32 v135, v147, v135
	v_add_f32 v135, v148, v135
	v_add_f32 v135, v149, v135
	v_add_f32 v135, v150, v135
	v_add_f32 v135, v151, v135
	v_add_f32 v135, v156, v135
	v_add_f32 v135, v157, v135
	v_add_f32 v135, v158, v135
	v_add_f32 v135, v159, v135
	v_add_f32 v135, v160, v135
	v_add_f32 v135, v161, v135
	v_add_f32 v135, v162, v135
	v_add_f32 v135, v163, v135
	v_add_f32 v135, v164, v135
	v_add_f32 v135, v55, v135
	v_mov_b32_e32 v127, s28
	v_mov_b32_e32 v146, s22
	v_cvt_pk_bf16_f32 v52, v158, v159
	v_cvt_pk_bf16_f32 v53, v160, v161
	v_cvt_pk_bf16_f32 v54, v162, v163
	s_waitcnt lgkmcnt(1)
	v_mfma_f32_32x32x16_bf16 v[0:15], v[88:91], v[48:51], v[0:15]
	v_add_u32_e32 v48, s31, v136
	v_med3_i32 v48, v48, 0, v236
	v_add_u32_e32 v48, 0x100, v48
	v_mov_b32_e32 v49, s31
	v_cndmask_b32_e32 v192, v48, v49, vcc
	v_add_u32_e32 v126, v192, v134
	s_movk_i32 s31, 0x100
	v_cmp_gt_u32_e32 vcc, s31, v126
	s_movk_i32 s31, 0xf8
	v_cvt_pk_bf16_f32 v55, v164, v55
	v_cndmask_b32_e32 v48, v127, v146, vcc
	v_add_u32_e32 v48, v48, v126
	v_mad_i64_i32 v[166:167], s[42:43], v48, s20, v[130:131]
	v_mfma_f32_32x32x16_bf16 v[16:31], v[84:87], v[52:55], v[16:31]
	global_load_dwordx4 v[84:87], v[166:167], off
	v_lshl_add_u64 v[124:125], v[192:193], 1, v[128:129]
	v_lshl_add_u64 v[166:167], v[166:167], 0, s[46:47]
	global_load_dwordx4 v[88:91], v[166:167], off
	s_waitcnt lgkmcnt(0)
	v_mfma_f32_32x32x16_bf16 v[0:15], v[80:83], v[52:55], v[0:15]
	global_load_dwordx4 v[80:83], v[124:125], off
	s_waitcnt vmcnt(9)
	ds_write_b128 v138, v[112:115] offset:8192
	ds_write_b128 v139, v[116:119] offset:12800
	s_waitcnt vmcnt(8)
	ds_write_b128 v138, v[120:123] offset:9344
	s_waitcnt vmcnt(7)
	ds_write_b128 v139, v[92:95] offset:14080
	s_waitcnt vmcnt(6)
	ds_write_b128 v138, v[96:99] offset:10496
	s_waitcnt vmcnt(5)
	ds_write_b128 v139, v[100:103] offset:15360
	s_waitcnt vmcnt(4)
	ds_write_b128 v138, v[104:107] offset:11648
	s_waitcnt vmcnt(3)
	ds_write_b128 v139, v[108:111] offset:16640
	ds_read_b128 v[100:103], v140 offset:8192
	ds_read_b128 v[104:107], v140 offset:8224
	v_add_co_u32_e32 v48, vcc, s61, v124
	s_movk_i32 s31, 0xf0
	s_nop 0
	v_addc_co_u32_e32 v49, vcc, 0, v125, vcc
	global_load_dwordx4 v[92:95], v[48:49], off
	s_movk_i32 s31, 0xe8
	v_lshl_add_u64 v[166:167], v[166:167], 0, s[46:47]
	global_load_dwordx4 v[96:99], v[166:167], off
	s_waitcnt lgkmcnt(1)
	v_mfma_f32_32x32x16_bf16 v[48:63], v[100:103], v[72:75], v[32:47]
	v_add_co_u32_e32 v100, vcc, s62, v124
	s_nop 1
	v_addc_co_u32_e32 v101, vcc, 0, v125, vcc
	global_load_dwordx4 v[100:103], v[100:101], off
	s_waitcnt lgkmcnt(0)
	v_mfma_f32_32x32x16_bf16 v[48:63], v[104:107], v[64:67], v[48:63]
	ds_read_b128 v[108:111], v140 offset:8256
	ds_read_b128 v[146:149], v140 offset:8288
	v_lshl_add_u64 v[166:167], v[166:167], 0, s[46:47]
	v_add_co_u32_e32 v112, vcc, s64, v124
	global_load_dwordx4 v[104:107], v[166:167], off
	s_nop 0
	v_addc_co_u32_e32 v113, vcc, 0, v125, vcc
	s_waitcnt lgkmcnt(1)
	v_mfma_f32_32x32x16_bf16 v[48:63], v[108:111], v[68:71], v[48:63]
	global_load_dwordx4 v[108:111], v[112:113], off
	ds_read_b128 v[120:123], v141 offset:12800
	ds_read_b128 v[112:115], v141 offset:12832
	ds_read_b128 v[124:127], v141 offset:15360
	ds_read_b128 v[116:119], v141 offset:15392
	s_sub_u32 s100, s29, 8
	s_cmp_lt_u32 s100, 7
	s_cselect_b64 s[100:101], s[98:99], 0
	s_andn2_b64 s[100:101], s[24:25], s[100:101]
	s_and_b64 vcc, exec, s[100:101]
	s_waitcnt lgkmcnt(4)
	v_mfma_f32_32x32x16_bf16 v[48:63], v[146:149], v[76:79], v[48:63]
	s_cbranch_vccz .LBB0_427
	s_add_i32 s24, s29, 1
	s_cmp_lt_u32 s24, 17
	s_movk_i32 s29, 0x4000
	s_cselect_b64 s[24:25], -1, 0
	v_cmp_gt_u32_e32 vcc, s29, v142
	v_add_u32_e32 v142, 0xffffff00, v143
	s_movk_i32 s29, 0x101
	s_and_b64 s[24:25], s[24:25], vcc
	v_cmp_gt_u32_e32 vcc, s29, v142
	s_and_b64 vcc, s[24:25], vcc
	v_add_u32_e32 v146, 0xffffff01, v143
	v_cndmask_b32_e32 v142, v237, v48, vcc
	v_cmp_gt_u32_e32 vcc, s29, v146
	s_and_b64 vcc, s[24:25], vcc
	v_add_u32_e32 v147, 0xffffff02, v143
	v_cndmask_b32_e32 v146, v237, v49, vcc
	v_cmp_gt_u32_e32 vcc, s29, v147
	s_and_b64 vcc, s[24:25], vcc
	v_add_u32_e32 v148, 0xffffff03, v143
	v_cndmask_b32_e32 v147, v237, v50, vcc
	v_cmp_gt_u32_e32 vcc, s29, v148
	s_and_b64 vcc, s[24:25], vcc
	v_add_u32_e32 v149, 0xffffff04, v143
	v_cndmask_b32_e32 v148, v237, v51, vcc
	v_cmp_gt_u32_e32 vcc, s29, v149
	s_and_b64 vcc, s[24:25], vcc
	v_add_u32_e32 v150, 0xffffff05, v143
	v_cndmask_b32_e32 v149, v237, v52, vcc
	v_cmp_gt_u32_e32 vcc, s29, v150
	s_and_b64 vcc, s[24:25], vcc
	v_add_u32_e32 v151, 0xffffff06, v143
	v_cndmask_b32_e32 v150, v237, v53, vcc
	v_cmp_gt_u32_e32 vcc, s29, v151
	s_and_b64 vcc, s[24:25], vcc
	v_add_u32_e32 v156, 0xffffff07, v143
	v_cndmask_b32_e32 v151, v237, v54, vcc
	v_cmp_gt_u32_e32 vcc, s29, v156
	s_and_b64 vcc, s[24:25], vcc
	v_add_u32_e32 v158, 0xffffff11, v143
	v_cndmask_b32_e32 v156, v237, v55, vcc
	v_exp_f32_e32 v157, v156
	v_add_u32_e32 v156, 0xffffff10, v143
	v_cmp_gt_u32_e32 vcc, s29, v156
	s_and_b64 vcc, s[24:25], vcc
	v_add_u32_e32 v159, 0xffffff12, v143
	v_cndmask_b32_e32 v156, v237, v56, vcc
	v_cmp_gt_u32_e32 vcc, s29, v158
	s_and_b64 vcc, s[24:25], vcc
	v_add_u32_e32 v160, 0xffffff13, v143
	v_cndmask_b32_e32 v158, v237, v57, vcc
	v_cmp_gt_u32_e32 vcc, s29, v159
	s_and_b64 vcc, s[24:25], vcc
	v_add_u32_e32 v161, 0xffffff14, v143
	v_cndmask_b32_e32 v159, v237, v58, vcc
	v_cmp_gt_u32_e32 vcc, s29, v160
	s_and_b64 vcc, s[24:25], vcc
	v_add_u32_e32 v162, 0xffffff15, v143
	v_cndmask_b32_e32 v160, v237, v59, vcc
	v_cmp_gt_u32_e32 vcc, s29, v161
	s_and_b64 vcc, s[24:25], vcc
	v_add_u32_e32 v163, 0xffffff16, v143
	v_cndmask_b32_e32 v161, v237, v60, vcc
	v_cmp_gt_u32_e32 vcc, s29, v162
	s_and_b64 vcc, s[24:25], vcc
	v_add_u32_e32 v143, 0xffffff17, v143
	v_cndmask_b32_e32 v162, v237, v61, vcc
	v_cmp_gt_u32_e32 vcc, s29, v163
	s_and_b64 vcc, s[24:25], vcc
	v_exp_f32_e32 v142, v142
	v_cndmask_b32_e32 v163, v237, v62, vcc
	v_cmp_gt_u32_e32 vcc, s29, v143
	s_and_b64 vcc, s[24:25], vcc
	v_exp_f32_e32 v146, v146
	v_exp_f32_e32 v147, v147
	v_exp_f32_e32 v148, v148
	v_exp_f32_e32 v149, v149
	v_exp_f32_e32 v150, v150
	v_exp_f32_e32 v151, v151
	v_exp_f32_e32 v156, v156
	v_exp_f32_e32 v158, v158
	v_exp_f32_e32 v159, v159
	v_exp_f32_e32 v160, v160
	v_exp_f32_e32 v161, v161
	v_exp_f32_e32 v162, v162
	v_exp_f32_e32 v163, v163
	v_cndmask_b32_e32 v63, v237, v63, vcc
	s_cbranch_execnz .LBB0_420
	s_branch .LBB0_428
